# same as previous but the static priority raise is on waves 4-7 (mirror)
# speedup vs baseline: 1.0183x; 1.0087x over previous
; __device__ __forceinline__ int swz(int row) { return ((row & 3) << 2) | ((row >> 2) & 3); }
; __device__ __forceinline__ void dma_tile(const bf16* kbase, const bf16* vbase, int key0, ldsp stage, int wave, int lane) {
;     ...
;     for (int j = 0; j < 2; ++j) { const int rowb = 8 * wave + 4 * j, row = rowb + (lane >> 4), cc = (lane & 15) ^ swz(row); const size_t off = (size_t)(key0 + row) * 128 + cc * 8;
;         glds16(kbase + off, sb + rowb * 256);
;         glds16(vbase + off, sb + RKV + rowb * 256); }
; __device__ __forceinline__ void diff_unit(const bf16* proj, bf16* og0, const float* nwv, float lam_full, float one_m_li, int h, int qb, ldsp lds, int tid, int lane, int wave, int mode) {
;     ...
;     for (int i = 2; i < nt; ++i) {
;         asm volatile("s_waitcnt vmcnt(8)" ::: "memory");
;         __builtin_amdgcn_s_barrier();
;         asm volatile("" ::: "memory");
;         { int n = i + 3; n = n < nt ? n : nt - 1; dma_tile(kbase, vbase, 64 * (n - 2), lds + ((i + 3) & 3) * RSTG, wave, lane); }
;         ldsp Ks = lds + (i & 3) * RSTG, Vs = Ks + RKV;
;         flash_fast_tile2<4>(Ks, Vs, M, qf, o, mc, l);
.LBB0_433:
	s_mov_b32 s6, 2
	s_add_i32 s7, s9, 2
	s_or_b32 s8, s9, 1
	s_cmp_lt_u32 5, s7
	s_cselect_b32 s1, 5, s8
	v_lshl_add_u32 v230, s1, 6, v183
	v_add_u32_e32 v231, s35, v230
	v_add_u32_e32 v230, s31, v230
	v_lshlrev_b32_e32 v231, 8, v231
	v_lshlrev_b32_e32 v230, 8, v230
	v_lshl_add_u32 v231, v156, 1, v231
	v_lshl_add_u32 v230, v154, 1, v230
	s_and_b64 vcc, exec, s[20:21]
	s_cbranch_vccz .Lap_skip1
	s_setprio 1

; __device__ __forceinline__ int swz(int row) { return ((row & 3) << 2) | ((row >> 2) & 3); }
; __device__ __forceinline__ void dma_tile(const bf16* kbase, const bf16* vbase, int key0, ldsp stage, int wave, int lane) {
;     ...
;     for (int j = 0; j < 2; ++j) { const int rowb = 8 * wave + 4 * j, row = rowb + (lane >> 4), cc = (lane & 15) ^ swz(row); const size_t off = (size_t)(key0 + row) * 128 + cc * 8;
;         glds16(kbase + off, sb + rowb * 256);
;         glds16(vbase + off, sb + RKV + rowb * 256); }
; __device__ __forceinline__ void diff_unit(const bf16* proj, bf16* og0, const float* nwv, float lam_full, float one_m_li, int h, int qb, ldsp lds, int tid, int lane, int wave, int mode) {
;     ...
;     for (int i = 2; i < nt; ++i) {
;         asm volatile("s_waitcnt vmcnt(8)" ::: "memory");
;         __builtin_amdgcn_s_barrier();
;         asm volatile("" ::: "memory");
;         { int n = i + 3; n = n < nt ? n : nt - 1; dma_tile(kbase, vbase, 64 * (n - 2), lds + ((i + 3) & 3) * RSTG, wave, lane); }
;         ldsp Ks = lds + (i & 3) * RSTG, Vs = Ks + RKV;
;         flash_fast_tile2<4>(Ks, Vs, M, qf, o, mc, l);
.LBB0_456:
	s_andn2_b64 vcc, exec, s[28:29]
	s_cbranch_vccnz .LBB0_465
	s_mov_b32 s6, 2
	s_cmp_lt_i32 5, s59
	s_cselect_b32 s1, 5, s60
	v_lshl_add_u32 v160, s1, 6, v183
	v_add_u32_e32 v161, s35, v160
	v_add_u32_e32 v160, s31, v160
	v_lshlrev_b32_e32 v161, 8, v161
	v_lshlrev_b32_e32 v160, 8, v160
	v_lshl_add_u32 v161, v156, 1, v161
	v_lshl_add_u32 v160, v154, 1, v160
	s_and_b64 vcc, exec, s[20:21]
	s_cbranch_vccz .Lap_skip2
	s_setprio 1
